# streaming (nt) stores for the write-once final output in the fused final rmsnorm pass
# baseline (speedup 1.0000x reference)
.Lof_w:
	s_barrier
	v_mbcnt_lo_u32_b32 v200, -1, 0
	v_mbcnt_hi_u32_b32 v200, -1, v200
	v_and_b32_e32 v201, 7, v200
	v_lshlrev_b32_e32 v201, 2, v201
	v_lshrrev_b32_e32 v202, 4, v200
	s_lshr_b32 s36, s3, 6
	s_and_b32 s38, s36, 3
	s_lshr_b32 s37, s36, 2
	s_lshl_b32 s40, s38, 10
	v_lshl_add_u32 v245, v202, 5, s40
	v_add_u32_e32 v245, v201, v245
	s_lshl_b32 s40, s96, 5
	s_add_u32 s44, s87, s40
	s_addc_u32 s45, s19, 0
	s_add_u32 s46, s44, 0x1000
	s_addc_u32 s47, s45, 0
	v_mov_b32_e32 v216, 0
	v_mov_b32_e32 v217, 0
	v_mov_b32_e32 v218, 0
	v_mov_b32_e32 v219, 0
	v_mov_b32_e32 v220, 0
	v_mov_b32_e32 v221, 0
	v_mov_b32_e32 v222, 0
	v_mov_b32_e32 v223, 0
	v_mov_b32_e32 v224, 0
	v_mov_b32_e32 v225, 0
	v_mov_b32_e32 v226, 0
	v_mov_b32_e32 v227, 0
	v_mov_b32_e32 v228, 0
	v_mov_b32_e32 v229, 0
	v_mov_b32_e32 v230, 0
	v_mov_b32_e32 v231, 0
	s_mov_b32 exec_lo, 0xff00ff
	s_mov_b32 exec_hi, 0xff00ff
	global_load_dword v216, v245, s[44:45]
	global_load_dword v217, v245, s[44:45] offset:128
	global_load_dword v218, v245, s[44:45] offset:256
	global_load_dword v219, v245, s[44:45] offset:384
	global_load_dword v220, v245, s[44:45] offset:512
	global_load_dword v221, v245, s[44:45] offset:640
	global_load_dword v222, v245, s[44:45] offset:768
	global_load_dword v223, v245, s[44:45] offset:896
	global_load_dword v224, v245, s[46:47]
	global_load_dword v225, v245, s[46:47] offset:128
	global_load_dword v226, v245, s[46:47] offset:256
	global_load_dword v227, v245, s[46:47] offset:384
	global_load_dword v228, v245, s[46:47] offset:512
	global_load_dword v229, v245, s[46:47] offset:640
	global_load_dword v230, v245, s[46:47] offset:768
	global_load_dword v231, v245, s[46:47] offset:896
	s_mov_b64 exec, -1
	v_readlane_b32 s40, v254, 39
	v_readlane_b32 s41, v254, 40
	v_and_b32_e32 v201, 15, v200
	s_lshl_b32 s36, s37, 8
	s_lshl_b32 s38, s94, 2
	s_add_i32 s36, s36, s38
	v_lshl_add_u32 v201, v201, 4, s36
	global_load_dwordx4 v[184:187], v201, s[40:41]
	global_load_dwordx4 v[188:191], v201, s[40:41] offset:512
	v_readlane_b32 s40, v254, 41
	v_readlane_b32 s41, v254, 42
	s_lshl_b32 s36, s96, 12
	s_add_u32 s36, s36, s38
	s_add_u32 s48, s40, s36
	s_addc_u32 s49, s41, 0
	v_mov_b32_e32 v203, 0x358637bd
	s_waitcnt vmcnt(2)
	v_add_f32_dpp v216, v216, v216 row_ror:8 row_mask:0xf bank_mask:0xf
	v_add_f32_dpp v217, v217, v217 row_ror:8 row_mask:0xf bank_mask:0xf
	v_add_f32_dpp v218, v218, v218 row_ror:8 row_mask:0xf bank_mask:0xf
	v_add_f32_dpp v219, v219, v219 row_ror:8 row_mask:0xf bank_mask:0xf
	v_add_f32_dpp v220, v220, v220 row_ror:8 row_mask:0xf bank_mask:0xf
	v_add_f32_dpp v221, v221, v221 row_ror:8 row_mask:0xf bank_mask:0xf
	v_add_f32_dpp v222, v222, v222 row_ror:8 row_mask:0xf bank_mask:0xf
	v_add_f32_dpp v223, v223, v223 row_ror:8 row_mask:0xf bank_mask:0xf
	v_add_f32_dpp v224, v224, v224 row_ror:8 row_mask:0xf bank_mask:0xf
	v_add_f32_dpp v225, v225, v225 row_ror:8 row_mask:0xf bank_mask:0xf
	v_add_f32_dpp v226, v226, v226 row_ror:8 row_mask:0xf bank_mask:0xf
	v_add_f32_dpp v227, v227, v227 row_ror:8 row_mask:0xf bank_mask:0xf
	v_add_f32_dpp v228, v228, v228 row_ror:8 row_mask:0xf bank_mask:0xf
	v_add_f32_dpp v229, v229, v229 row_ror:8 row_mask:0xf bank_mask:0xf
	v_add_f32_dpp v230, v230, v230 row_ror:8 row_mask:0xf bank_mask:0xf
	v_add_f32_dpp v231, v231, v231 row_ror:8 row_mask:0xf bank_mask:0xf
	v_add_f32_dpp v216, v216, v216 row_ror:4 row_mask:0xf bank_mask:0xf
	v_add_f32_dpp v217, v217, v217 row_ror:4 row_mask:0xf bank_mask:0xf
	v_add_f32_dpp v218, v218, v218 row_ror:4 row_mask:0xf bank_mask:0xf
	v_add_f32_dpp v219, v219, v219 row_ror:4 row_mask:0xf bank_mask:0xf
	v_add_f32_dpp v220, v220, v220 row_ror:4 row_mask:0xf bank_mask:0xf
	v_add_f32_dpp v221, v221, v221 row_ror:4 row_mask:0xf bank_mask:0xf
	v_add_f32_dpp v222, v222, v222 row_ror:4 row_mask:0xf bank_mask:0xf
	v_add_f32_dpp v223, v223, v223 row_ror:4 row_mask:0xf bank_mask:0xf
	v_add_f32_dpp v224, v224, v224 row_ror:4 row_mask:0xf bank_mask:0xf
	v_add_f32_dpp v225, v225, v225 row_ror:4 row_mask:0xf bank_mask:0xf
	v_add_f32_dpp v226, v226, v226 row_ror:4 row_mask:0xf bank_mask:0xf
	v_add_f32_dpp v227, v227, v227 row_ror:4 row_mask:0xf bank_mask:0xf
	v_add_f32_dpp v228, v228, v228 row_ror:4 row_mask:0xf bank_mask:0xf
	v_add_f32_dpp v229, v229, v229 row_ror:4 row_mask:0xf bank_mask:0xf
	v_add_f32_dpp v230, v230, v230 row_ror:4 row_mask:0xf bank_mask:0xf
	v_add_f32_dpp v231, v231, v231 row_ror:4 row_mask:0xf bank_mask:0xf
	v_add_f32_dpp v216, v216, v216 row_ror:2 row_mask:0xf bank_mask:0xf
	v_add_f32_dpp v217, v217, v217 row_ror:2 row_mask:0xf bank_mask:0xf
	v_add_f32_dpp v218, v218, v218 row_ror:2 row_mask:0xf bank_mask:0xf
	v_add_f32_dpp v219, v219, v219 row_ror:2 row_mask:0xf bank_mask:0xf
	v_add_f32_dpp v220, v220, v220 row_ror:2 row_mask:0xf bank_mask:0xf
	v_add_f32_dpp v221, v221, v221 row_ror:2 row_mask:0xf bank_mask:0xf
	v_add_f32_dpp v222, v222, v222 row_ror:2 row_mask:0xf bank_mask:0xf
	v_add_f32_dpp v223, v223, v223 row_ror:2 row_mask:0xf bank_mask:0xf
	v_add_f32_dpp v224, v224, v224 row_ror:2 row_mask:0xf bank_mask:0xf
	v_add_f32_dpp v225, v225, v225 row_ror:2 row_mask:0xf bank_mask:0xf
	v_add_f32_dpp v226, v226, v226 row_ror:2 row_mask:0xf bank_mask:0xf
	v_add_f32_dpp v227, v227, v227 row_ror:2 row_mask:0xf bank_mask:0xf
	v_add_f32_dpp v228, v228, v228 row_ror:2 row_mask:0xf bank_mask:0xf
	v_add_f32_dpp v229, v229, v229 row_ror:2 row_mask:0xf bank_mask:0xf
	v_add_f32_dpp v230, v230, v230 row_ror:2 row_mask:0xf bank_mask:0xf
	v_add_f32_dpp v231, v231, v231 row_ror:2 row_mask:0xf bank_mask:0xf
	v_add_f32_dpp v216, v216, v216 row_ror:1 row_mask:0xf bank_mask:0xf
	v_add_f32_dpp v217, v217, v217 row_ror:1 row_mask:0xf bank_mask:0xf
	v_add_f32_dpp v218, v218, v218 row_ror:1 row_mask:0xf bank_mask:0xf
	v_add_f32_dpp v219, v219, v219 row_ror:1 row_mask:0xf bank_mask:0xf
	v_add_f32_dpp v220, v220, v220 row_ror:1 row_mask:0xf bank_mask:0xf
	v_add_f32_dpp v221, v221, v221 row_ror:1 row_mask:0xf bank_mask:0xf
	v_add_f32_dpp v222, v222, v222 row_ror:1 row_mask:0xf bank_mask:0xf
	v_add_f32_dpp v223, v223, v223 row_ror:1 row_mask:0xf bank_mask:0xf
	v_add_f32_dpp v224, v224, v224 row_ror:1 row_mask:0xf bank_mask:0xf
	v_add_f32_dpp v225, v225, v225 row_ror:1 row_mask:0xf bank_mask:0xf
	v_add_f32_dpp v226, v226, v226 row_ror:1 row_mask:0xf bank_mask:0xf
	v_add_f32_dpp v227, v227, v227 row_ror:1 row_mask:0xf bank_mask:0xf
	v_add_f32_dpp v228, v228, v228 row_ror:1 row_mask:0xf bank_mask:0xf
	v_add_f32_dpp v229, v229, v229 row_ror:1 row_mask:0xf bank_mask:0xf
	v_add_f32_dpp v230, v230, v230 row_ror:1 row_mask:0xf bank_mask:0xf
	v_add_f32_dpp v231, v231, v231 row_ror:1 row_mask:0xf bank_mask:0xf
	v_fmamk_f32 v216, v216, 0x3a800000, v203
	v_fmamk_f32 v217, v217, 0x3a800000, v203
	v_fmamk_f32 v218, v218, 0x3a800000, v203
	v_fmamk_f32 v219, v219, 0x3a800000, v203
	v_fmamk_f32 v220, v220, 0x3a800000, v203
	v_fmamk_f32 v221, v221, 0x3a800000, v203
	v_fmamk_f32 v222, v222, 0x3a800000, v203
	v_fmamk_f32 v223, v223, 0x3a800000, v203
	v_fmamk_f32 v224, v224, 0x3a800000, v203
	v_fmamk_f32 v225, v225, 0x3a800000, v203
	v_fmamk_f32 v226, v226, 0x3a800000, v203
	v_fmamk_f32 v227, v227, 0x3a800000, v203
	v_fmamk_f32 v228, v228, 0x3a800000, v203
	v_fmamk_f32 v229, v229, 0x3a800000, v203
	v_fmamk_f32 v230, v230, 0x3a800000, v203
	v_fmamk_f32 v231, v231, 0x3a800000, v203
	v_rsq_f32_e32 v216, v216
	v_rsq_f32_e32 v217, v217
	v_rsq_f32_e32 v218, v218
	v_rsq_f32_e32 v219, v219
	v_rsq_f32_e32 v220, v220
	v_rsq_f32_e32 v221, v221
	v_rsq_f32_e32 v222, v222
	v_rsq_f32_e32 v223, v223
	v_rsq_f32_e32 v224, v224
	v_rsq_f32_e32 v225, v225
	v_rsq_f32_e32 v226, v226
	v_rsq_f32_e32 v227, v227
	v_rsq_f32_e32 v228, v228
	v_rsq_f32_e32 v229, v229
	v_rsq_f32_e32 v230, v230
	v_rsq_f32_e32 v231, v231
	s_waitcnt vmcnt(0)
	s_add_u32 s38, s48, 0x0
	s_addc_u32 s39, s49, 0
	v_mul_f32_e32 v48, v48, v216
	v_mul_f32_e32 v49, v49, v216
	v_mul_f32_e32 v50, v50, v216
	v_mul_f32_e32 v51, v51, v216
	v_pk_mul_f32 v[48:49], v[48:49], v[184:185]
	v_pk_mul_f32 v[50:51], v[50:51], v[186:187]
	v_mul_f32_e32 v116, v116, v217
	v_mul_f32_e32 v117, v117, v217
	v_mul_f32_e32 v118, v118, v217
	v_mul_f32_e32 v119, v119, v217
	v_pk_mul_f32 v[116:117], v[116:117], v[184:185]
	v_pk_mul_f32 v[118:119], v[118:119], v[186:187]
	v_mul_f32_e32 v124, v124, v218
	v_mul_f32_e32 v125, v125, v218
	v_mul_f32_e32 v126, v126, v218
	v_mul_f32_e32 v127, v127, v218
	v_pk_mul_f32 v[124:125], v[124:125], v[184:185]
	v_pk_mul_f32 v[126:127], v[126:127], v[186:187]
	v_mul_f32_e32 v108, v108, v219
	v_mul_f32_e32 v109, v109, v219
	v_mul_f32_e32 v110, v110, v219
	v_mul_f32_e32 v111, v111, v219
	v_pk_mul_f32 v[108:109], v[108:109], v[184:185]
	v_pk_mul_f32 v[110:111], v[110:111], v[186:187]
	global_store_dwordx4 v232, v[48:51], s[38:39] nt
	global_store_dwordx4 v233, v[116:119], s[38:39] nt
	global_store_dwordx4 v234, v[124:127], s[38:39] nt
	global_store_dwordx4 v235, v[108:111], s[38:39] nt
	s_add_u32 s38, s48, 0x10000
	s_addc_u32 s39, s49, 0
	v_mul_f32_e32 v60, v60, v220
	v_mul_f32_e32 v61, v61, v220
	v_mul_f32_e32 v62, v62, v220
	v_mul_f32_e32 v63, v63, v220
	v_pk_mul_f32 v[60:61], v[60:61], v[184:185]
	v_pk_mul_f32 v[62:63], v[62:63], v[186:187]
	v_mul_f32_e32 v88, v88, v221
	v_mul_f32_e32 v89, v89, v221
	v_mul_f32_e32 v90, v90, v221
	v_mul_f32_e32 v91, v91, v221
	v_pk_mul_f32 v[88:89], v[88:89], v[184:185]
	v_pk_mul_f32 v[90:91], v[90:91], v[186:187]
	v_mul_f32_e32 v120, v120, v222
	v_mul_f32_e32 v121, v121, v222
	v_mul_f32_e32 v122, v122, v222
	v_mul_f32_e32 v123, v123, v222
	v_pk_mul_f32 v[120:121], v[120:121], v[184:185]
	v_pk_mul_f32 v[122:123], v[122:123], v[186:187]
	v_mul_f32_e32 v100, v100, v223
	v_mul_f32_e32 v101, v101, v223
	v_mul_f32_e32 v102, v102, v223
	v_mul_f32_e32 v103, v103, v223
	v_pk_mul_f32 v[100:101], v[100:101], v[184:185]
	v_pk_mul_f32 v[102:103], v[102:103], v[186:187]
	global_store_dwordx4 v232, v[60:63], s[38:39] nt
	global_store_dwordx4 v233, v[88:91], s[38:39] nt
	global_store_dwordx4 v234, v[120:123], s[38:39] nt
	global_store_dwordx4 v235, v[100:103], s[38:39] nt
	s_add_u32 s38, s48, 0x80000
	s_addc_u32 s39, s49, 0
	v_mul_f32_e32 v52, v52, v224
	v_mul_f32_e32 v53, v53, v224
	v_mul_f32_e32 v54, v54, v224
	v_mul_f32_e32 v55, v55, v224
	v_pk_mul_f32 v[52:53], v[52:53], v[184:185]
	v_pk_mul_f32 v[54:55], v[54:55], v[186:187]
	v_mul_f32_e32 v84, v84, v225
	v_mul_f32_e32 v85, v85, v225
	v_mul_f32_e32 v86, v86, v225
	v_mul_f32_e32 v87, v87, v225
	v_pk_mul_f32 v[84:85], v[84:85], v[184:185]
	v_pk_mul_f32 v[86:87], v[86:87], v[186:187]
	v_mul_f32_e32 v112, v112, v226
	v_mul_f32_e32 v113, v113, v226
	v_mul_f32_e32 v114, v114, v226
	v_mul_f32_e32 v115, v115, v226
	v_pk_mul_f32 v[112:113], v[112:113], v[184:185]
	v_pk_mul_f32 v[114:115], v[114:115], v[186:187]
	v_mul_f32_e32 v96, v96, v227
	v_mul_f32_e32 v97, v97, v227
	v_mul_f32_e32 v98, v98, v227
	v_mul_f32_e32 v99, v99, v227
	v_pk_mul_f32 v[96:97], v[96:97], v[184:185]
	v_pk_mul_f32 v[98:99], v[98:99], v[186:187]
	global_store_dwordx4 v232, v[52:55], s[38:39] nt
	global_store_dwordx4 v233, v[84:87], s[38:39] nt
	global_store_dwordx4 v234, v[112:115], s[38:39] nt
	global_store_dwordx4 v235, v[96:99], s[38:39] nt
	s_add_u32 s38, s48, 0x90000
	s_addc_u32 s39, s49, 0
	v_mul_f32_e32 v40, v40, v228
	v_mul_f32_e32 v41, v41, v228
	v_mul_f32_e32 v42, v42, v228
	v_mul_f32_e32 v43, v43, v228
	v_pk_mul_f32 v[40:41], v[40:41], v[184:185]
	v_pk_mul_f32 v[42:43], v[42:43], v[186:187]
	v_mul_f32_e32 v76, v76, v229
	v_mul_f32_e32 v77, v77, v229
	v_mul_f32_e32 v78, v78, v229
	v_mul_f32_e32 v79, v79, v229
	v_pk_mul_f32 v[76:77], v[76:77], v[184:185]
	v_pk_mul_f32 v[78:79], v[78:79], v[186:187]
	v_mul_f32_e32 v104, v104, v230
	v_mul_f32_e32 v105, v105, v230
	v_mul_f32_e32 v106, v106, v230
	v_mul_f32_e32 v107, v107, v230
	v_pk_mul_f32 v[104:105], v[104:105], v[184:185]
	v_pk_mul_f32 v[106:107], v[106:107], v[186:187]
	v_mul_f32_e32 v92, v92, v231
	v_mul_f32_e32 v93, v93, v231
	v_mul_f32_e32 v94, v94, v231
	v_mul_f32_e32 v95, v95, v231
	v_pk_mul_f32 v[92:93], v[92:93], v[184:185]
	v_pk_mul_f32 v[94:95], v[94:95], v[186:187]
	global_store_dwordx4 v232, v[40:43], s[38:39] nt
	global_store_dwordx4 v233, v[76:79], s[38:39] nt
	global_store_dwordx4 v234, v[104:107], s[38:39] nt
	global_store_dwordx4 v235, v[92:95], s[38:39] nt
	s_add_u32 s38, s48, 0x200
	s_addc_u32 s39, s49, 0
	v_mul_f32_e32 v80, v80, v216
	v_mul_f32_e32 v81, v81, v216
	v_mul_f32_e32 v82, v82, v216
	v_mul_f32_e32 v83, v83, v216
	v_pk_mul_f32 v[80:81], v[80:81], v[188:189]
	v_pk_mul_f32 v[82:83], v[82:83], v[190:191]
	v_mul_f32_e32 v56, v56, v217
	v_mul_f32_e32 v57, v57, v217
	v_mul_f32_e32 v58, v58, v217
	v_mul_f32_e32 v59, v59, v217
	v_pk_mul_f32 v[56:57], v[56:57], v[188:189]
	v_pk_mul_f32 v[58:59], v[58:59], v[190:191]
	v_mul_f32_e32 v28, v28, v218
	v_mul_f32_e32 v29, v29, v218
	v_mul_f32_e32 v30, v30, v218
	v_mul_f32_e32 v31, v31, v218
	v_pk_mul_f32 v[28:29], v[28:29], v[188:189]
	v_pk_mul_f32 v[30:31], v[30:31], v[190:191]
	v_mul_f32_e32 v12, v12, v219
	v_mul_f32_e32 v13, v13, v219
	v_mul_f32_e32 v14, v14, v219
	v_mul_f32_e32 v15, v15, v219
	v_pk_mul_f32 v[12:13], v[12:13], v[188:189]
	v_pk_mul_f32 v[14:15], v[14:15], v[190:191]
	global_store_dwordx4 v232, v[80:83], s[38:39] nt
	global_store_dwordx4 v233, v[56:59], s[38:39] nt
	global_store_dwordx4 v234, v[28:31], s[38:39] nt
	global_store_dwordx4 v235, v[12:15], s[38:39] nt
	s_add_u32 s38, s48, 0x10200
	s_addc_u32 s39, s49, 0
	v_mul_f32_e32 v72, v72, v220
	v_mul_f32_e32 v73, v73, v220
	v_mul_f32_e32 v74, v74, v220
	v_mul_f32_e32 v75, v75, v220
	v_pk_mul_f32 v[72:73], v[72:73], v[188:189]
	v_pk_mul_f32 v[74:75], v[74:75], v[190:191]
	v_mul_f32_e32 v44, v44, v221
	v_mul_f32_e32 v45, v45, v221
	v_mul_f32_e32 v46, v46, v221
	v_mul_f32_e32 v47, v47, v221
	v_pk_mul_f32 v[44:45], v[44:45], v[188:189]
	v_pk_mul_f32 v[46:47], v[46:47], v[190:191]
	v_mul_f32_e32 v24, v24, v222
	v_mul_f32_e32 v25, v25, v222
	v_mul_f32_e32 v26, v26, v222
	v_mul_f32_e32 v27, v27, v222
	v_pk_mul_f32 v[24:25], v[24:25], v[188:189]
	v_pk_mul_f32 v[26:27], v[26:27], v[190:191]
	v_mul_f32_e32 v8, v8, v223
	v_mul_f32_e32 v9, v9, v223
	v_mul_f32_e32 v10, v10, v223
	v_mul_f32_e32 v11, v11, v223
	v_pk_mul_f32 v[8:9], v[8:9], v[188:189]
	v_pk_mul_f32 v[10:11], v[10:11], v[190:191]
	global_store_dwordx4 v232, v[72:75], s[38:39] nt
	global_store_dwordx4 v233, v[44:47], s[38:39] nt
	global_store_dwordx4 v234, v[24:27], s[38:39] nt
	global_store_dwordx4 v235, v[8:11], s[38:39] nt
	s_add_u32 s38, s48, 0x80200
	s_addc_u32 s39, s49, 0
	v_mul_f32_e32 v68, v68, v224
	v_mul_f32_e32 v69, v69, v224
	v_mul_f32_e32 v70, v70, v224
	v_mul_f32_e32 v71, v71, v224
	v_pk_mul_f32 v[68:69], v[68:69], v[188:189]
	v_pk_mul_f32 v[70:71], v[70:71], v[190:191]
	v_mul_f32_e32 v36, v36, v225
	v_mul_f32_e32 v37, v37, v225
	v_mul_f32_e32 v38, v38, v225
	v_mul_f32_e32 v39, v39, v225
	v_pk_mul_f32 v[36:37], v[36:37], v[188:189]
	v_pk_mul_f32 v[38:39], v[38:39], v[190:191]
	v_mul_f32_e32 v20, v20, v226
	v_mul_f32_e32 v21, v21, v226
	v_mul_f32_e32 v22, v22, v226
	v_mul_f32_e32 v23, v23, v226
	v_pk_mul_f32 v[20:21], v[20:21], v[188:189]
	v_pk_mul_f32 v[22:23], v[22:23], v[190:191]
	v_mul_f32_e32 v4, v4, v227
	v_mul_f32_e32 v5, v5, v227
	v_mul_f32_e32 v6, v6, v227
	v_mul_f32_e32 v7, v7, v227
	v_pk_mul_f32 v[4:5], v[4:5], v[188:189]
	v_pk_mul_f32 v[6:7], v[6:7], v[190:191]
	global_store_dwordx4 v232, v[68:71], s[38:39] nt
	global_store_dwordx4 v233, v[36:39], s[38:39] nt
	global_store_dwordx4 v234, v[20:23], s[38:39] nt
	global_store_dwordx4 v235, v[4:7], s[38:39] nt
	s_add_u32 s38, s48, 0x90200
	s_addc_u32 s39, s49, 0
	v_mul_f32_e32 v64, v64, v228
	v_mul_f32_e32 v65, v65, v228
	v_mul_f32_e32 v66, v66, v228
	v_mul_f32_e32 v67, v67, v228
	v_pk_mul_f32 v[64:65], v[64:65], v[188:189]
	v_pk_mul_f32 v[66:67], v[66:67], v[190:191]
	v_mul_f32_e32 v32, v32, v229
	v_mul_f32_e32 v33, v33, v229
	v_mul_f32_e32 v34, v34, v229
	v_mul_f32_e32 v35, v35, v229
	v_pk_mul_f32 v[32:33], v[32:33], v[188:189]
	v_pk_mul_f32 v[34:35], v[34:35], v[190:191]
	v_mul_f32_e32 v16, v16, v230
	v_mul_f32_e32 v17, v17, v230
	v_mul_f32_e32 v18, v18, v230
	v_mul_f32_e32 v19, v19, v230
	v_pk_mul_f32 v[16:17], v[16:17], v[188:189]
	v_pk_mul_f32 v[18:19], v[18:19], v[190:191]
	v_mul_f32_e32 v0, v0, v231
	v_mul_f32_e32 v1, v1, v231
	v_mul_f32_e32 v2, v2, v231
	v_mul_f32_e32 v3, v3, v231
	v_pk_mul_f32 v[0:1], v[0:1], v[188:189]
	v_pk_mul_f32 v[2:3], v[2:3], v[190:191]
	global_store_dwordx4 v232, v[64:67], s[38:39] nt
	global_store_dwordx4 v233, v[32:35], s[38:39] nt
	global_store_dwordx4 v234, v[16:19], s[38:39] nt
	global_store_dwordx4 v235, v[0:3], s[38:39] nt
	s_endpgm
